# relaxed K-loop LDS-DMA waits to per-phase vmcnt(10); conv units moved off the sgu blocks (40 conv-only blocks take 3-4 units)
# speedup vs baseline: 1.0167x; 1.0167x over previous
.LBB0_29:
	v_writelane_b32 v254, s6, 46
	s_mul_hi_i32 s69, s0, 17
	s_mov_b64 s[4:5], -1
	v_writelane_b32 v254, s7, 47
	v_writelane_b32 v254, s3, 48
	v_writelane_b32 v254, s24, 49
	s_mov_b32 s6, s0
	s_cmp_lt_i32 s33, 2
	v_writelane_b32 v254, s25, 50
	v_writelane_b32 v254, s26, 51
	v_writelane_b32 v254, s27, 52
	v_writelane_b32 v254, s0, 53
	s_mul_i32 s68, s6, 17
	s_nop 0
	v_writelane_b32 v254, s1, 54
	s_cbranch_scc1 .LBB0_269
	s_cmp_lt_i32 s33, 3
	s_cbranch_scc1 .LBB0_263
	s_cmp_lg_u32 s33, 3
	s_cbranch_scc0 .LBB0_82
	v_readlane_b32 s0, v254, 48
	s_cmp_lg_u32 s0, 1
	s_cbranch_scc1 .LBB0_81
	v_readlane_b32 s0, v254, 53
	s_cmp_eq_u32 s0, 3
	v_readlane_b32 s1, v254, 54
	s_cselect_b64 s[16:17], -1, 0
	s_and_b64 s[0:1], s[16:17], exec
	s_movk_i32 s0, 0x120
	s_cselect_b32 s0, 0x100, s0
	v_readlane_b32 s1, v253, 23
	s_cmp_ge_i32 s1, s0
	s_cbranch_scc1 .LBB0_72
	v_readlane_b32 s22, v254, 41
	v_readlane_b32 s23, v254, 42
	s_load_dwordx2 s[4:5], s[22:23], 0x120
	v_readlane_b32 s6, v254, 53
	s_bitcmp1_b32 s6, 0
	v_readlane_b32 s1, v254, 45
	s_cselect_b64 s[18:19], -1, 0
	s_bitcmp1_b32 s1, 0
	s_cselect_b32 s1, 0x5a00000, 0
	s_waitcnt lgkmcnt(0)
	s_add_u32 s1, s4, s1
	s_mov_b32 s24, s6
	s_addc_u32 s6, s5, 0
	s_load_dwordx8 s[8:15], s[22:23], 0xa8
	s_add_u32 s20, s1, 0x11198100
	s_addc_u32 s21, s6, 0
	s_add_u32 s22, s4, 0x1c598100
	s_addc_u32 s23, s5, 0
	s_mul_i32 s4, s24, 0xf800
	s_mul_hi_i32 s1, s24, 0xf800
	s_waitcnt lgkmcnt(0)
	s_add_u32 s8, s8, s4
	s_addc_u32 s9, s9, s1
	s_lshl_b32 s24, s24, 9
	s_ashr_i32 s25, s24, 31
	s_lshl_b64 s[4:5], s[24:25], 2
	s_add_u32 s12, s12, s4
	s_addc_u32 s13, s13, s5
	s_add_u32 s14, s14, s4
	s_addc_u32 s15, s15, s5
	v_readlane_b32 s1, v253, 23
	v_readlane_b32 s7, v254, 54
	s_nop 3
	s_mov_b32 s32, s1
	s_cmpk_ge_i32 s1, 0x70
	s_cbranch_scc1 .LBB0_36
	s_cmpk_ge_i32 s1, 40
	s_cbranch_scc1 .LBB0_72
	s_bitset1_b32 s32, 16
	s_branch .LBB0_36
.LBB0_35:
	s_or_b64 exec, exec, s[4:5]
	s_bitcmp1_b32 s32, 16
	s_cbranch_scc0 .Lconv_std
	s_add_i32 s32, s32, 40
	s_and_b32 s1, s32, 0xffff
	s_add_i32 s4, s0, 0xffffff70
	s_cmp_ge_i32 s1, s4
	s_cbranch_scc1 .LBB0_72
	s_cmpk_lt_i32 s1, 0x70
	s_cbranch_scc1 .LBB0_36
	s_addk_i32 s1, 0x90
	s_branch .LBB0_36
.Lconv_std:
	s_add_i32 s1, s1, s54
	s_cmp_ge_i32 s1, s0
	s_cbranch_scc1 .LBB0_72

.LBB0_376:
	s_add_i32 vcc_hi, s10, 2
	s_add_u32 s56, s4, 0x80
	s_addc_u32 s11, s5, 0
	s_add_i32 s98, 0, 0x10000
	v_add_u32_e32 v1, s98, v238
	ds_read_b128 v[132:135], v1
	ds_read_b128 v[136:139], v1 offset:1024
	ds_read_b128 v[140:143], v1 offset:2048
	ds_read_b128 v[144:147], v1 offset:3072
	s_cmp_eq_u32 s75, s10
	s_cselect_b32 s10, s50, s56
	s_cselect_b32 s11, s51, s11
	s_cselect_b32 s57, s97, vcc_lo
	s_cselect_b32 s56, s96, s1
	v_lshl_add_u64 v[180:181], s[4:5], 0, v[206:207]
	s_add_i32 m0, s73, 0xc000
	ds_read_b128 v[148:151], v240
	ds_read_b128 v[152:155], v240 offset:1024
	ds_read_b128 v[156:159], v240 offset:2048
	ds_read_b128 v[160:163], v240 offset:3072
	ds_read_b128 v[164:167], v240 offset:4096
	ds_read_b128 v[168:171], v240 offset:5120
	ds_read_b128 v[172:175], v240 offset:6144
	ds_read_b128 v[176:179], v240 offset:7168
	global_load_lds_dwordx4 v[180:181], off
	v_lshl_add_u64 v[180:181], s[4:5], 0, v[208:209]
	s_add_i32 m0, s73, 0xe000
	s_nop 0
	global_load_lds_dwordx4 v[180:181], off
	s_waitcnt lgkmcnt(8)
	s_waitcnt vmcnt(10)
	s_barrier
	s_waitcnt lgkmcnt(0)
	s_setprio 1
	s_waitcnt lgkmcnt(0)
	v_mfma_f32_16x16x32_f16 v[124:127], v[132:135], v[148:151], v[124:127]
	v_mfma_f32_16x16x32_f16 v[128:131], v[140:143], v[148:151], v[128:131]
	v_mfma_f32_16x16x32_f16 v[108:111], v[132:135], v[156:159], v[108:111]
	v_mfma_f32_16x16x32_f16 v[112:115], v[140:143], v[156:159], v[112:115]
	v_mfma_f32_16x16x32_f16 v[92:95], v[132:135], v[164:167], v[92:95]
	v_mfma_f32_16x16x32_f16 v[96:99], v[140:143], v[164:167], v[96:99]
	v_mfma_f32_16x16x32_f16 v[76:79], v[132:135], v[172:175], v[76:79]
	v_mfma_f32_16x16x32_f16 v[80:83], v[140:143], v[172:175], v[80:83]
	v_mfma_f32_16x16x32_f16 v[124:127], v[136:139], v[152:155], v[124:127]
	v_mfma_f32_16x16x32_f16 v[128:131], v[144:147], v[152:155], v[128:131]
	v_mfma_f32_16x16x32_f16 v[108:111], v[136:139], v[160:163], v[108:111]
	v_mfma_f32_16x16x32_f16 v[112:115], v[144:147], v[160:163], v[112:115]
	v_mfma_f32_16x16x32_f16 v[92:95], v[136:139], v[168:171], v[92:95]
	v_mfma_f32_16x16x32_f16 v[96:99], v[144:147], v[168:171], v[96:99]
	v_mfma_f32_16x16x32_f16 v[76:79], v[136:139], v[176:179], v[76:79]
	v_mfma_f32_16x16x32_f16 v[80:83], v[144:147], v[176:179], v[80:83]
	s_setprio 0
	s_barrier
	s_add_i32 s98, s98, s72
	v_add_u32_e32 v1, s58, v238
	v_lshl_add_u64 v[210:211], s[56:57], 0, v[200:201]
	s_mov_b32 m0, s98
	ds_read_b128 v[180:183], v1
	ds_read_b128 v[184:187], v1 offset:1024
	ds_read_b128 v[188:191], v1 offset:2048
	ds_read_b128 v[192:195], v1 offset:3072
	global_load_lds_dwordx4 v[210:211], off
	v_lshl_add_u64 v[212:213], s[56:57], 0, v[202:203]
	s_add_i32 m0, s98, 0x2000
	s_nop 0
	global_load_lds_dwordx4 v[212:213], off
	s_waitcnt vmcnt(10)
	s_barrier
	s_waitcnt lgkmcnt(0)
	s_setprio 1
	s_waitcnt lgkmcnt(0)
	v_mfma_f32_16x16x32_f16 v[116:119], v[180:183], v[148:151], v[116:119]
	v_mfma_f32_16x16x32_f16 v[120:123], v[188:191], v[148:151], v[120:123]
	v_mfma_f32_16x16x32_f16 v[100:103], v[180:183], v[156:159], v[100:103]
	v_mfma_f32_16x16x32_f16 v[104:107], v[188:191], v[156:159], v[104:107]
	v_mfma_f32_16x16x32_f16 v[84:87], v[180:183], v[164:167], v[84:87]
	v_mfma_f32_16x16x32_f16 v[88:91], v[188:191], v[164:167], v[88:91]
	v_mfma_f32_16x16x32_f16 v[68:71], v[180:183], v[172:175], v[68:71]
	v_mfma_f32_16x16x32_f16 v[72:75], v[188:191], v[172:175], v[72:75]
	v_mfma_f32_16x16x32_f16 v[116:119], v[184:187], v[152:155], v[116:119]
	v_mfma_f32_16x16x32_f16 v[120:123], v[192:195], v[152:155], v[120:123]
	v_mfma_f32_16x16x32_f16 v[100:103], v[184:187], v[160:163], v[100:103]
	v_mfma_f32_16x16x32_f16 v[104:107], v[192:195], v[160:163], v[104:107]
	v_mfma_f32_16x16x32_f16 v[84:87], v[184:187], v[168:171], v[84:87]
	v_mfma_f32_16x16x32_f16 v[88:91], v[192:195], v[168:171], v[88:91]
	v_mfma_f32_16x16x32_f16 v[68:71], v[184:187], v[176:179], v[68:71]
	v_mfma_f32_16x16x32_f16 v[72:75], v[192:195], v[176:179], v[72:75]
	s_setprio 0
	s_mov_b32 m0, s73
	v_lshl_add_u64 v[214:215], s[10:11], 0, v[200:201]
	s_barrier
	ds_read_b128 v[148:151], v240 offset:16384
	ds_read_b128 v[152:155], v240 offset:17408
	ds_read_b128 v[156:159], v240 offset:18432
	ds_read_b128 v[160:163], v240 offset:19456
	ds_read_b128 v[164:167], v240 offset:20480
	ds_read_b128 v[168:171], v240 offset:21504
	ds_read_b128 v[172:175], v240 offset:22528
	ds_read_b128 v[176:179], v240 offset:23552
	global_load_lds_dwordx4 v[214:215], off
	v_lshl_add_u64 v[216:217], s[10:11], 0, v[202:203]
	s_mov_b32 m0, s78
	s_nop 0
	global_load_lds_dwordx4 v[216:217], off
	s_barrier
	s_waitcnt lgkmcnt(0)
	s_setprio 1
	s_waitcnt lgkmcnt(0)
	v_mfma_f32_16x16x32_f16 v[60:63], v[132:135], v[148:151], v[60:63]
	v_mfma_f32_16x16x32_f16 v[64:67], v[140:143], v[148:151], v[64:67]
	v_mfma_f32_16x16x32_f16 v[44:47], v[132:135], v[156:159], v[44:47]
	v_mfma_f32_16x16x32_f16 v[48:51], v[140:143], v[156:159], v[48:51]
	v_mfma_f32_16x16x32_f16 v[28:31], v[132:135], v[164:167], v[28:31]
	v_mfma_f32_16x16x32_f16 v[32:35], v[140:143], v[164:167], v[32:35]
	v_mfma_f32_16x16x32_f16 v[12:15], v[132:135], v[172:175], v[12:15]
	v_mfma_f32_16x16x32_f16 v[16:19], v[140:143], v[172:175], v[16:19]
	v_mfma_f32_16x16x32_f16 v[60:63], v[136:139], v[152:155], v[60:63]
	v_mfma_f32_16x16x32_f16 v[64:67], v[144:147], v[152:155], v[64:67]
	v_mfma_f32_16x16x32_f16 v[44:47], v[136:139], v[160:163], v[44:47]
	v_mfma_f32_16x16x32_f16 v[48:51], v[144:147], v[160:163], v[48:51]
	v_mfma_f32_16x16x32_f16 v[28:31], v[136:139], v[168:171], v[28:31]
	v_mfma_f32_16x16x32_f16 v[32:35], v[144:147], v[168:171], v[32:35]
	v_mfma_f32_16x16x32_f16 v[12:15], v[136:139], v[176:179], v[12:15]
	v_mfma_f32_16x16x32_f16 v[16:19], v[144:147], v[176:179], v[16:19]
	s_setprio 0
	s_barrier
	s_add_u32 s56, s56, s28
	s_addc_u32 s57, s57, s29
	s_add_i32 s98, s58, s72
	v_lshl_add_u64 v[218:219], s[56:57], 0, v[200:201]
	s_mov_b32 m0, s98
	v_lshl_add_u64 v[220:221], s[56:57], 0, v[202:203]
	global_load_lds_dwordx4 v[218:219], off
	s_add_i32 m0, s98, 0x2000
	s_nop 0
	global_load_lds_dwordx4 v[220:221], off
	s_waitcnt vmcnt(10)
	s_barrier
	s_setprio 1
	v_mfma_f32_16x16x32_f16 v[52:55], v[180:183], v[148:151], v[52:55]
	v_mfma_f32_16x16x32_f16 v[56:59], v[188:191], v[148:151], v[56:59]
	v_mfma_f32_16x16x32_f16 v[36:39], v[180:183], v[156:159], v[36:39]
	v_mfma_f32_16x16x32_f16 v[40:43], v[188:191], v[156:159], v[40:43]
	v_mfma_f32_16x16x32_f16 v[20:23], v[180:183], v[164:167], v[20:23]
	v_mfma_f32_16x16x32_f16 v[24:27], v[188:191], v[164:167], v[24:27]
	v_mfma_f32_16x16x32_f16 v[8:11], v[180:183], v[172:175], v[8:11]
	v_mfma_f32_16x16x32_f16 v[4:7], v[188:191], v[172:175], v[4:7]
	v_mfma_f32_16x16x32_f16 v[52:55], v[184:187], v[152:155], v[52:55]
	v_mfma_f32_16x16x32_f16 v[56:59], v[192:195], v[152:155], v[56:59]
	v_mfma_f32_16x16x32_f16 v[36:39], v[184:187], v[160:163], v[36:39]
	v_mfma_f32_16x16x32_f16 v[40:43], v[192:195], v[160:163], v[40:43]
	v_mfma_f32_16x16x32_f16 v[20:23], v[184:187], v[168:171], v[20:23]
	v_mfma_f32_16x16x32_f16 v[24:27], v[192:195], v[168:171], v[24:27]
	v_mfma_f32_16x16x32_f16 v[8:11], v[184:187], v[176:179], v[8:11]
	v_mfma_f32_16x16x32_f16 v[4:7], v[192:195], v[176:179], v[4:7]
	s_setprio 0
	v_add_u32_e32 v1, s99, v238
	s_barrier
	ds_read_b128 v[132:135], v1
	ds_read_b128 v[136:139], v1 offset:1024
	ds_read_b128 v[140:143], v1 offset:2048
	ds_read_b128 v[144:147], v1 offset:3072
	s_add_u32 s10, s10, s28
	s_addc_u32 s11, s11, s29
	s_mov_b32 m0, s79
	v_lshl_add_u64 v[180:181], s[10:11], 0, v[200:201]
	ds_read_b128 v[148:151], v240 offset:32768
	ds_read_b128 v[152:155], v240 offset:33792
	ds_read_b128 v[156:159], v240 offset:34816
	ds_read_b128 v[160:163], v240 offset:35840
	ds_read_b128 v[164:167], v240 offset:36864
	ds_read_b128 v[168:171], v240 offset:37888
	ds_read_b128 v[172:175], v240 offset:38912
	ds_read_b128 v[176:179], v240 offset:39936
	global_load_lds_dwordx4 v[180:181], off
	v_lshl_add_u64 v[180:181], s[10:11], 0, v[202:203]
	s_mov_b32 m0, s60
	s_nop 0
	global_load_lds_dwordx4 v[180:181], off
	s_waitcnt lgkmcnt(8)
	s_waitcnt vmcnt(10)
	s_barrier
	s_waitcnt lgkmcnt(0)
	s_setprio 1
	s_waitcnt lgkmcnt(0)
	v_mfma_f32_16x16x32_f16 v[124:127], v[132:135], v[148:151], v[124:127]
	v_mfma_f32_16x16x32_f16 v[128:131], v[140:143], v[148:151], v[128:131]
	v_mfma_f32_16x16x32_f16 v[108:111], v[132:135], v[156:159], v[108:111]
	v_mfma_f32_16x16x32_f16 v[112:115], v[140:143], v[156:159], v[112:115]
	v_mfma_f32_16x16x32_f16 v[92:95], v[132:135], v[164:167], v[92:95]
	v_mfma_f32_16x16x32_f16 v[96:99], v[140:143], v[164:167], v[96:99]
	v_mfma_f32_16x16x32_f16 v[76:79], v[132:135], v[172:175], v[76:79]
	v_mfma_f32_16x16x32_f16 v[80:83], v[140:143], v[172:175], v[80:83]
	v_mfma_f32_16x16x32_f16 v[124:127], v[136:139], v[152:155], v[124:127]
	v_mfma_f32_16x16x32_f16 v[128:131], v[144:147], v[152:155], v[128:131]
	v_mfma_f32_16x16x32_f16 v[108:111], v[136:139], v[160:163], v[108:111]
	v_mfma_f32_16x16x32_f16 v[112:115], v[144:147], v[160:163], v[112:115]
	v_mfma_f32_16x16x32_f16 v[92:95], v[136:139], v[168:171], v[92:95]
	v_mfma_f32_16x16x32_f16 v[96:99], v[144:147], v[168:171], v[96:99]
	v_mfma_f32_16x16x32_f16 v[76:79], v[136:139], v[176:179], v[76:79]
	v_mfma_f32_16x16x32_f16 v[80:83], v[144:147], v[176:179], v[80:83]
	s_setprio 0
	s_barrier
	s_add_i32 s10, 0, 0x1c000
	s_add_i32 s11, s99, s72
	v_add_u32_e32 v1, s10, v238
	v_lshl_add_u64 v[210:211], v[210:211], 0, s[86:87]
	s_mov_b32 m0, s11
	ds_read_b128 v[180:183], v1
	ds_read_b128 v[184:187], v1 offset:1024
	ds_read_b128 v[188:191], v1 offset:2048
	ds_read_b128 v[192:195], v1 offset:3072
	global_load_lds_dwordx4 v[210:211], off
	v_lshl_add_u64 v[210:211], v[212:213], 0, s[86:87]
	s_add_i32 m0, s11, 0x2000
	s_nop 0
	global_load_lds_dwordx4 v[210:211], off
	s_waitcnt vmcnt(10)
	s_barrier
	s_waitcnt lgkmcnt(0)
	s_setprio 1
	s_waitcnt lgkmcnt(0)
	v_mfma_f32_16x16x32_f16 v[116:119], v[180:183], v[148:151], v[116:119]
	v_mfma_f32_16x16x32_f16 v[120:123], v[188:191], v[148:151], v[120:123]
	v_mfma_f32_16x16x32_f16 v[100:103], v[180:183], v[156:159], v[100:103]
	v_mfma_f32_16x16x32_f16 v[104:107], v[188:191], v[156:159], v[104:107]
	v_mfma_f32_16x16x32_f16 v[84:87], v[180:183], v[164:167], v[84:87]
	v_mfma_f32_16x16x32_f16 v[88:91], v[188:191], v[164:167], v[88:91]
	v_mfma_f32_16x16x32_f16 v[68:71], v[180:183], v[172:175], v[68:71]
	v_mfma_f32_16x16x32_f16 v[72:75], v[188:191], v[172:175], v[72:75]
	v_mfma_f32_16x16x32_f16 v[116:119], v[184:187], v[152:155], v[116:119]
	v_mfma_f32_16x16x32_f16 v[120:123], v[192:195], v[152:155], v[120:123]
	v_mfma_f32_16x16x32_f16 v[100:103], v[184:187], v[160:163], v[100:103]
	v_mfma_f32_16x16x32_f16 v[104:107], v[192:195], v[160:163], v[104:107]
	v_mfma_f32_16x16x32_f16 v[84:87], v[184:187], v[168:171], v[84:87]
	v_mfma_f32_16x16x32_f16 v[88:91], v[192:195], v[168:171], v[88:91]
	v_mfma_f32_16x16x32_f16 v[68:71], v[184:187], v[176:179], v[68:71]
	v_mfma_f32_16x16x32_f16 v[72:75], v[192:195], v[176:179], v[72:75]
	s_setprio 0
	s_mov_b32 m0, s77
	v_lshl_add_u64 v[210:211], v[214:215], 0, s[86:87]
	s_barrier
	ds_read_b128 v[148:151], v240 offset:49152
	ds_read_b128 v[152:155], v240 offset:50176
	ds_read_b128 v[156:159], v240 offset:51200
	ds_read_b128 v[160:163], v240 offset:52224
	ds_read_b128 v[164:167], v240 offset:53248
	ds_read_b128 v[168:171], v240 offset:54272
	ds_read_b128 v[172:175], v240 offset:55296
	ds_read_b128 v[176:179], v240 offset:56320
	global_load_lds_dwordx4 v[210:211], off
	v_lshl_add_u64 v[210:211], v[216:217], 0, s[86:87]
	s_mov_b32 m0, s64
	s_nop 0
	global_load_lds_dwordx4 v[210:211], off
	s_barrier
	s_waitcnt lgkmcnt(0)
	s_setprio 1
	s_waitcnt lgkmcnt(0)
	v_mfma_f32_16x16x32_f16 v[60:63], v[132:135], v[148:151], v[60:63]
	v_mfma_f32_16x16x32_f16 v[64:67], v[140:143], v[148:151], v[64:67]
	v_mfma_f32_16x16x32_f16 v[44:47], v[132:135], v[156:159], v[44:47]
	v_mfma_f32_16x16x32_f16 v[48:51], v[140:143], v[156:159], v[48:51]
	v_mfma_f32_16x16x32_f16 v[28:31], v[132:135], v[164:167], v[28:31]
	v_mfma_f32_16x16x32_f16 v[32:35], v[140:143], v[164:167], v[32:35]
	v_mfma_f32_16x16x32_f16 v[12:15], v[132:135], v[172:175], v[12:15]
	v_mfma_f32_16x16x32_f16 v[16:19], v[140:143], v[172:175], v[16:19]
	v_mfma_f32_16x16x32_f16 v[60:63], v[136:139], v[152:155], v[60:63]
	v_mfma_f32_16x16x32_f16 v[64:67], v[144:147], v[152:155], v[64:67]
	v_mfma_f32_16x16x32_f16 v[44:47], v[136:139], v[160:163], v[44:47]
	v_mfma_f32_16x16x32_f16 v[48:51], v[144:147], v[160:163], v[48:51]
	v_mfma_f32_16x16x32_f16 v[28:31], v[136:139], v[168:171], v[28:31]
	v_mfma_f32_16x16x32_f16 v[32:35], v[144:147], v[168:171], v[32:35]
	v_mfma_f32_16x16x32_f16 v[12:15], v[136:139], v[176:179], v[12:15]
	v_mfma_f32_16x16x32_f16 v[16:19], v[144:147], v[176:179], v[16:19]
	s_setprio 0
	s_barrier
	s_add_i32 s10, s10, s72
	v_lshl_add_u64 v[132:133], v[218:219], 0, s[86:87]
	s_mov_b32 m0, s10
	s_nop 0
	global_load_lds_dwordx4 v[132:133], off
	v_lshl_add_u64 v[132:133], v[220:221], 0, s[86:87]
	s_add_i32 m0, s10, 0x2000
	s_nop 0
	global_load_lds_dwordx4 v[132:133], off
	s_waitcnt vmcnt(10)
	s_barrier
	s_setprio 1
	v_mfma_f32_16x16x32_f16 v[52:55], v[180:183], v[148:151], v[52:55]
	v_mfma_f32_16x16x32_f16 v[56:59], v[188:191], v[148:151], v[56:59]
	v_mfma_f32_16x16x32_f16 v[36:39], v[180:183], v[156:159], v[36:39]
	v_mfma_f32_16x16x32_f16 v[40:43], v[188:191], v[156:159], v[40:43]
	v_mfma_f32_16x16x32_f16 v[20:23], v[180:183], v[164:167], v[20:23]
	v_mfma_f32_16x16x32_f16 v[24:27], v[188:191], v[164:167], v[24:27]
	v_mfma_f32_16x16x32_f16 v[8:11], v[180:183], v[172:175], v[8:11]
	v_mfma_f32_16x16x32_f16 v[4:7], v[188:191], v[172:175], v[4:7]
	v_mfma_f32_16x16x32_f16 v[52:55], v[184:187], v[152:155], v[52:55]
	v_mfma_f32_16x16x32_f16 v[56:59], v[192:195], v[152:155], v[56:59]
	v_mfma_f32_16x16x32_f16 v[36:39], v[184:187], v[160:163], v[36:39]
	v_mfma_f32_16x16x32_f16 v[40:43], v[192:195], v[160:163], v[40:43]
	v_mfma_f32_16x16x32_f16 v[20:23], v[184:187], v[168:171], v[20:23]
	v_mfma_f32_16x16x32_f16 v[24:27], v[192:195], v[168:171], v[24:27]
	v_mfma_f32_16x16x32_f16 v[8:11], v[184:187], v[176:179], v[8:11]
	v_mfma_f32_16x16x32_f16 v[4:7], v[192:195], v[176:179], v[4:7]
	s_setprio 0
	s_add_u32 s4, s4, 0x100
	s_addc_u32 s5, s5, 0
	s_add_u32 s1, s1, 0x100
	s_addc_u32 vcc_lo, vcc_lo, 0
	s_cmp_ge_i32 vcc_hi, s67
	s_mov_b32 s10, vcc_hi
	s_barrier
	s_cbranch_scc0 .LBB0_376
